# two-gate-tile workgroups run a second conversion pass over the HGRN workgroups' item family; HGRN workgroups convert nothing
# baseline (speedup 1.0000x reference)
;     ...
;     { int it = (PART == 0 ? gw : I_IN + gw); const int end = (PART == 0 ? I_IN : (I_IN + it_last < NITEMS ? I_IN + it_last : NITEMS));
;       if (it < end) {
;         ConvItem pa = conv_item(a, ws, it), pb = pa; float wa[32], wb[32]; f32x4 ka[2], kb[2];
;         conv_load(pa, wa, ka, lane);
;         for (;;) {
;             const bool hb = it + NGW < end; if (hb) { pb = conv_item(a, ws, it + NGW); conv_load(pb, wb, kb, lane); }
;             conv_finish(pa, wa, ka, scr, lane);
;             if (!hb) break; it += NGW;
;             const bool ha = it + NGW < end; if (ha) { pa = conv_item(a, ws, it + NGW); conv_load(pa, wa, ka, lane); }
;             conv_finish(pb, wb, kb, scr, lane);
;             if (!ha) break; it += NGW;
;         }
;       }
;     }
.LBB0_416:
	s_mov_b64 s[2:3], -1
	s_and_b64 vcc, exec, s[0:1]
	s_cbranch_vccz .LBB0_511
	s_mov_b32 s100, 0
	s_lshl_b32 s0, s33, 3
	v_readlane_b32 s1, v254, 11
	s_add_i32 s0, s0, s1
	s_addk_i32 s0, 0xfe00
.Lmy_cv2:
	s_cmpk_gt_i32 s0, 0x167f
	s_cbranch_scc1 .LBB0_510
	s_add_i32 s40, s0, 0x1200
	s_cmp_gt_i32 s0, -1
	s_cbranch_scc0 .LBB0_425
	s_cmpk_gt_u32 s40, 0x13ff
	s_cbranch_scc0 .LBB0_426
	s_cmpk_gt_u32 s40, 0x15ff
	s_cbranch_scc0 .LBB0_427
	s_cmpk_gt_u32 s40, 0x17ff
	s_cbranch_scc0 .LBB0_428
	s_cmpk_gt_u32 s40, 0x22ff
	s_cbranch_scc0 .LBB0_429
	s_add_u32 s8, s72, 0x2500000
	s_addc_u32 s9, s73, 0
	s_lshl_b32 s0, s40, 1
	s_add_i32 s0, s0, 0x7fffba00
	s_and_b32 s4, s0, 0x7fffffc0
	s_lshl_b32 s0, s40, 5
	s_and_b32 s10, s0, 0x3e0
	s_mov_b64 s[6:7], 0
	s_mov_b64 s[0:1], 0
	s_mov_b64 s[2:3], s[68:69]
	s_branch .LBB0_430

;     ...
;     { int it = (PART == 0 ? gw : I_IN + gw); const int end = (PART == 0 ? I_IN : (I_IN + it_last < NITEMS ? I_IN + it_last : NITEMS));
;       if (it < end) {
;         ConvItem pa = conv_item(a, ws, it), pb = pa; float wa[32], wb[32]; f32x4 ka[2], kb[2];
;         conv_load(pa, wa, ka, lane);
;         for (;;) {
;             const bool hb = it + NGW < end; if (hb) { pb = conv_item(a, ws, it + NGW); conv_load(pb, wb, kb, lane); }
;             conv_finish(pa, wa, ka, scr, lane);
;             if (!hb) break; it += NGW;
;             const bool ha = it + NGW < end; if (ha) { pa = conv_item(a, ws, it + NGW); conv_load(pa, wa, ka, lane); }
;             conv_finish(pb, wb, kb, scr, lane);
;             if (!ha) break; it += NGW;
;         }
;       }
;     }
.LBB0_510:
	s_cmp_lg_u32 s100, 0
	s_cbranch_scc1 .Lmy_cv_done
	s_mov_b32 s100, 1
	s_lshl_b32 s0, s33, 3
	v_readlane_b32 s1, v254, 11
	s_add_i32 s0, s0, s1
	s_branch .Lmy_cv2

; __global__ void __launch_bounds__(NTHREADS, 2) hybrid_fwd(Args args) {
;     ...
;             if ((int)blockIdx.x < 64) { hgrn_v2(args, lds, (int)blockIdx.x, 64); p0_prologue<1>(args, lds, wave, lane, 2048 + 512 + (int)blockIdx.x * NWAVES + wave, 1024); S.l0 = -1; S.l1 = -1; S.l2 = -1; }
.LBB0_580:
	s_lshl_b32 s0, s33, 3
	v_readlane_b32 s1, v254, 11
	s_add_i32 s0, s0, s1
	s_movk_i32 s0, 0x7fff
	s_cmpk_gt_i32 s0, 0x167f
	s_cbranch_scc1 .LBB0_666
	s_add_i32 s38, s0, 0x1200
	s_cmp_gt_i32 s0, -1
	s_cbranch_scc0 .LBB0_587
	s_cmpk_gt_u32 s38, 0x13ff
	s_cbranch_scc0 .LBB0_588
	s_cmpk_gt_u32 s38, 0x15ff
	s_cbranch_scc0 .LBB0_589
	s_cmpk_gt_u32 s38, 0x17ff
	s_cbranch_scc0 .LBB0_590
	s_cmpk_gt_u32 s38, 0x22ff
	s_cbranch_scc0 .LBB0_591
	s_add_u32 s8, s72, 0x2500000
	s_addc_u32 s9, s73, 0
	s_lshl_b32 s0, s38, 1
	s_add_i32 s0, s0, 0x7fffba00
	s_and_b32 s4, s0, 0x7fffffc0
	s_lshl_b32 s0, s38, 5
	s_and_b32 s10, s0, 0x3e0
	s_mov_b64 s[6:7], 0
	s_mov_b64 s[0:1], 0
	s_mov_b64 s[2:3], s[68:69]
	s_branch .LBB0_592
